# waves 4-7 branch around their dummy second K-chunk load in the MLA loop (4 fewer dwordx4 VMEM wave-instructions per tile)
# speedup vs baseline: 1.0116x; 1.0074x over previous
; __device__ __forceinline__ void softmax_blk(f32x16& p0, f32x16& p1, f32x16& o0, f32x16& o1, float& mhat, float& lrun, u32x4 (&pf)[4], bool first) {
;     float r0 = max2_(p0[0], p0[1]), r1 = max2_(p1[0], p1[1]);
; #pragma unroll
; __device__ __forceinline__ void attn_unit(const bf16_t* Qh, const bf16_t* Kh, const bf16_t* Vh, bf16_t* Oh  , int S, int qb, LAS unsigned char* lds, int tid) {
;     ...
;     const bool has1 = tid < 256; const int kc0 = tid, kc1 = has1 ? tid + 512 : tid;
;     const unsigned kd0 = (unsigned)((kc0 / 12) * KPITCH + (kc0 % 12) * 16);
;     const unsigned kd1 = has1 ? (unsigned)((kc1 / 12) * KPITCH + (kc1 % 12) * 16) : (unsigned)(DUMMY + (tid - 256) * 16);
;     const unsigned kd1n = has1 ? BUF : 0u;
;     const unsigned vd = (unsigned)(KBYTES + ((tid & 7) >> 2) * 4096 + (tid >> 3) * 64 + (tid & 3) * 16);
;     const GAS u32x4* Kg = (const GAS u32x4*)Kh; const GAS u32x4* Vg = (const GAS u32x4*)Vh;
;     const int NT = S >> 6;
;     u32x4 ka = GLD(u32x4, Kg + kc0), kb = GLD(u32x4, Kg + kc1), va = GLD(u32x4, Vg + tid);
;     *(LAS u32x4*)(lds + kd0) = ka; *(LAS u32x4*)(lds + kd1) = kb; *(LAS u32x4*)(lds + vd) = va;
;     __syncthreads();
;     f32x16 oa0 = {}, oa1 = {}, ob0 = {}, ob1 = {}; float ma = 0.f, la = 0.f, mb = 0.f, lb = 0.f;
;     const unsigned kfo = (unsigned)(r32 * KPITCH + hi * 16);
;     const unsigned vb = (unsigned)(KBYTES + ((lane >> 4) & 1) * 32 + (lane & 3) * 8 + (4 * hi + ((lane & 15) >> 2)) * 64);
;     for (int t = 0; t < NT; ++t) {
;         const unsigned cur = (unsigned)(t & 1) * BUF, nxt = BUF - cur;
;         const int tn = t + 1 < NT ? t + 1 : t;
;         ka = GLD(u32x4, Kg + (size_t)tn * 768 + kc0); kb = GLD(u32x4, Kg + (size_t)tn * 768 + kc1); va = GLD(u32x4, Vg + (size_t)tn * 512 + tid);
;         u32x4 pf[4];
;         {
;             f32x16 p0 = {}, p1 = {};
; #pragma unroll
;             for (int s = 0; s < 6; ++s) {
;                 const bf16x8 a0 = *(const LAS bf16x8*)(lds + cur + kfo + s * 32), a1 = *(const LAS bf16x8*)(lds + cur + kfo + 32 * KPITCH + s * 32);
;                 const bf16x8 q = *(const LAS bf16x8*)(ql + s * 1024);
;                 p0 = __builtin_amdgcn_mfma_f32_32x32x16_bf16(a0, q, p0, 0, 0, 0); p1 = __builtin_amdgcn_mfma_f32_32x32x16_bf16(a1, q, p1, 0, 0, 0);
;             }
;             softmax_blk(p0, p1, oa0, oa1, ma, la, pf, t == 0);
.Lmla_prio:
	s_add_u32 s100, s100, 0x2000
	s_addc_u32 s101, s101, 0
	ds_read_b128 v[128:131], v155
	ds_read_b128 v[142:145], v155 offset:6656
	ds_read_b128 v[162:165], v135 offset:43008
	ds_read_b128 v[176:179], v155 offset:32
	ds_read_b128 v[180:183], v155 offset:6688
	ds_read_b128 v[186:189], v135 offset:44032
	s_waitcnt lgkmcnt(3)
	v_mfma_f32_32x32x16_bf16 v[64:79], v[128:131], v[162:165], 0
	v_mfma_f32_32x32x16_bf16 v[80:95], v[142:145], v[162:165], 0
	ds_read_b128 v[128:131], v155 offset:64
	ds_read_b128 v[142:145], v155 offset:6720
	ds_read_b128 v[162:165], v135 offset:45056
	global_load_dwordx4 v[218:221], v171, s[26:27]
	s_cmp_eq_u64 s[36:37], 0
	s_cbranch_scc1 .Lmla_nok1p
	global_load_dwordx4 v[222:225], v184, s[26:27]
.Lmla_nok1p:
	s_add_u32 s26, s26, 0x3000
	s_addc_u32 s27, s27, 0
	s_waitcnt lgkmcnt(3)
	v_mfma_f32_32x32x16_bf16 v[64:79], v[176:179], v[186:189], v[64:79]
	v_mfma_f32_32x32x16_bf16 v[80:95], v[180:183], v[186:189], v[80:95]
	ds_read_b128 v[176:179], v155 offset:96
	ds_read_b128 v[180:183], v155 offset:6752
	ds_read_b128 v[186:189], v135 offset:46080
	s_waitcnt lgkmcnt(3)
	v_mfma_f32_32x32x16_bf16 v[64:79], v[128:131], v[162:165], v[64:79]
	v_mfma_f32_32x32x16_bf16 v[80:95], v[142:145], v[162:165], v[80:95]
	ds_read_b128 v[128:131], v155 offset:128
	ds_read_b128 v[142:145], v155 offset:6784
	ds_read_b128 v[162:165], v135 offset:47104
	s_waitcnt lgkmcnt(3)
	v_mfma_f32_32x32x16_bf16 v[64:79], v[176:179], v[186:189], v[64:79]
	v_mfma_f32_32x32x16_bf16 v[80:95], v[180:183], v[186:189], v[80:95]
	ds_read_b128 v[176:179], v155 offset:160
	ds_read_b128 v[180:183], v155 offset:6816
	ds_read_b128 v[186:189], v135 offset:48128
	s_waitcnt lgkmcnt(3)
	v_mfma_f32_32x32x16_bf16 v[64:79], v[128:131], v[162:165], v[64:79]
	v_mfma_f32_32x32x16_bf16 v[80:95], v[142:145], v[162:165], v[80:95]
	ds_read_b128 v[128:131], v155
	ds_read_b128 v[142:145], v155 offset:6656
	ds_read_b128 v[162:165], v135 offset:49152
	s_waitcnt lgkmcnt(3)
	v_mfma_f32_32x32x16_bf16 v[64:79], v[176:179], v[186:189], v[64:79]
	v_mfma_f32_32x32x16_bf16 v[80:95], v[180:183], v[186:189], v[80:95]
	ds_read_b128 v[176:179], v155 offset:32
	ds_read_b128 v[180:183], v155 offset:6688
	ds_read_b128 v[186:189], v135 offset:50176
	s_waitcnt lgkmcnt(3)
	v_mfma_f32_32x32x16_bf16 v[96:111], v[128:131], v[162:165], 0
	v_mfma_f32_32x32x16_bf16 v[112:127], v[142:145], v[162:165], 0
	ds_read_b128 v[128:131], v155 offset:64
	ds_read_b128 v[142:145], v155 offset:6720
	ds_read_b128 v[162:165], v135 offset:51200
	s_nop 5
	v_max3_f32 v248, v64, v65, v66
	v_max3_f32 v249, v80, v81, v82
	v_max3_f32 v248, v248, v67, v68
	v_max3_f32 v249, v249, v83, v84
	v_max3_f32 v248, v248, v69, v70
	v_max3_f32 v249, v249, v85, v86
	v_max3_f32 v248, v248, v71, v72
	v_max3_f32 v249, v249, v87, v88
	v_max3_f32 v248, v248, v73, v74
	v_max3_f32 v249, v249, v89, v90
	v_max3_f32 v248, v248, v75, v76
	v_max3_f32 v249, v249, v91, v92
	v_max3_f32 v248, v248, v77, v78
	v_max3_f32 v249, v249, v93, v94
	v_max3_f32 v248, v248, v79, v95
	v_max_f32_e32 v248, v248, v249
	v_mov_b32_e32 v251, v248
	s_nop 1
	v_permlane32_swap_b32_e32 v248, v251
	v_max_f32_e32 v167, v248, v251
	v_sub_f32_e32 v64, v64, v167
	v_sub_f32_e32 v65, v65, v167
	v_sub_f32_e32 v66, v66, v167
	v_sub_f32_e32 v67, v67, v167
	v_sub_f32_e32 v68, v68, v167
	v_sub_f32_e32 v69, v69, v167
	v_sub_f32_e32 v70, v70, v167
	v_sub_f32_e32 v71, v71, v167
	v_sub_f32_e32 v72, v72, v167
	v_sub_f32_e32 v73, v73, v167
	v_sub_f32_e32 v74, v74, v167
	v_sub_f32_e32 v75, v75, v167
	v_sub_f32_e32 v76, v76, v167
	v_sub_f32_e32 v77, v77, v167
	s_waitcnt lgkmcnt(3)
	v_mfma_f32_32x32x16_bf16 v[96:111], v[176:179], v[186:189], v[96:111]
	v_mfma_f32_32x32x16_bf16 v[112:127], v[180:183], v[186:189], v[112:127]
	ds_read_b128 v[176:179], v155 offset:96
	ds_read_b128 v[180:183], v155 offset:6752
	ds_read_b128 v[186:189], v135 offset:52224
	v_sub_f32_e32 v78, v78, v167
	v_sub_f32_e32 v79, v79, v167
	v_sub_f32_e32 v80, v80, v167
	v_sub_f32_e32 v81, v81, v167
	v_sub_f32_e32 v82, v82, v167
	v_sub_f32_e32 v83, v83, v167
	v_sub_f32_e32 v84, v84, v167
	v_sub_f32_e32 v85, v85, v167
	v_sub_f32_e32 v86, v86, v167
	v_sub_f32_e32 v87, v87, v167
	v_sub_f32_e32 v88, v88, v167
	v_sub_f32_e32 v89, v89, v167
	v_sub_f32_e32 v90, v90, v167
	v_sub_f32_e32 v91, v91, v167
	v_sub_f32_e32 v92, v92, v167
	v_sub_f32_e32 v93, v93, v167
	v_sub_f32_e32 v94, v94, v167
	v_sub_f32_e32 v95, v95, v167
	v_sub_f32_e32 v232, 0, v167
	v_sub_f32_e32 v233, 0, v167
	v_sub_f32_e32 v234, 0, v167
	v_sub_f32_e32 v235, 0, v167
	v_sub_f32_e32 v236, 0, v167
	v_sub_f32_e32 v237, 0, v167
	v_sub_f32_e32 v238, 0, v167
	v_sub_f32_e32 v239, 0, v167
	v_sub_f32_e32 v240, 0, v167
	v_sub_f32_e32 v241, 0, v167
	v_sub_f32_e32 v242, 0, v167
	v_sub_f32_e32 v243, 0, v167
	v_sub_f32_e32 v244, 0, v167
	v_sub_f32_e32 v245, 0, v167
	v_sub_f32_e32 v246, 0, v167
	v_sub_f32_e32 v247, 0, v167
	s_waitcnt lgkmcnt(3)
	v_mfma_f32_32x32x16_bf16 v[96:111], v[128:131], v[162:165], v[96:111]
	v_mfma_f32_32x32x16_bf16 v[112:127], v[142:145], v[162:165], v[112:127]
	ds_read_b128 v[128:131], v155 offset:128
	ds_read_b128 v[142:145], v155 offset:6784
	ds_read_b128 v[162:165], v135 offset:53248
	v_max3_f32 v248, v64, v65, v66
	v_max3_f32 v249, v80, v81, v82
	v_max3_f32 v248, v248, v67, v68
	v_max3_f32 v249, v249, v83, v84
	v_max3_f32 v248, v248, v69, v70
	v_max3_f32 v249, v249, v85, v86
	v_max3_f32 v248, v248, v71, v72
	v_max3_f32 v249, v249, v87, v88
	v_max3_f32 v248, v248, v73, v74
	v_max3_f32 v249, v249, v89, v90
	v_max3_f32 v248, v248, v75, v76
	v_max3_f32 v249, v249, v91, v92
	v_max3_f32 v248, v248, v77, v78
	v_max3_f32 v249, v249, v93, v94
	v_max3_f32 v248, v248, v79, v95
	v_max_f32_e32 v248, v248, v249
	v_mov_b32_e32 v251, v248
	s_nop 1
	v_permlane32_swap_b32_e32 v248, v251
	v_max_f32_e32 v167, v248, v251
	v_cmp_lt_f32_e32 vcc, s72, v167
	s_cbranch_vccnz .Lmla_rescAp

; #define LAS __attribute__((address_space(3)))
; __device__ __forceinline__ float swap_max(float m) { auto rr = __builtin_amdgcn_permlane32_swap(__float_as_uint(m), __float_as_uint(m), false, false); return fmaxf(__uint_as_float(rr[0]), __uint_as_float(rr[1])); }
; __device__ __forceinline__ float max2_(float a, float b) { return __builtin_amdgcn_fmed3f(a, b, INFINITY); }
; __device__ __forceinline__ void softmax_blk(f32x16& p0, f32x16& p1, f32x16& o0, f32x16& o1, float& mhat, float& lrun, u32x4 (&pf)[4], bool first) {
;     float r0 = max2_(p0[0], p0[1]), r1 = max2_(p1[0], p1[1]);
; #pragma unroll
;     for (int e = 2; e < 16; ++e) { r0 = max2_(r0, p0[e]); r1 = max2_(r1, p1[e]); }
;     const float rm = swap_max(max2_(r0, r1));
;     if (first || __any(rm - mhat > THR)) {
;         const float mn = first ? rm : fmaxf(rm, mhat); const float f = first ? 0.f : __builtin_amdgcn_exp2f(mhat - mn); mhat = mn; lrun *= f;
; __device__ __forceinline__ void attn_unit(const bf16_t* Qh, const bf16_t* Kh, const bf16_t* Vh, bf16_t* Oh  , int S, int qb, LAS unsigned char* lds, int tid) {
;     ...
;         ka = GLD(u32x4, Kg + (size_t)tn * 768 + kc0); kb = GLD(u32x4, Kg + (size_t)tn * 768 + kc1); va = GLD(u32x4, Vg + (size_t)tn * 512 + tid);
;         u32x4 pf[4];
;         {
;             f32x16 p0 = {}, p1 = {};
; #pragma unroll
;             for (int s = 0; s < 6; ++s) {
;                 const bf16x8 a0 = *(const LAS bf16x8*)(lds + cur + kfo + s * 32), a1 = *(const LAS bf16x8*)(lds + cur + kfo + 32 * KPITCH + s * 32);
;                 const bf16x8 q = *(const LAS bf16x8*)(ql + s * 1024);
;                 p0 = __builtin_amdgcn_mfma_f32_32x32x16_bf16(a0, q, p0, 0, 0, 0); p1 = __builtin_amdgcn_mfma_f32_32x32x16_bf16(a1, q, p1, 0, 0, 0);
.Lmla_top:
	ds_read_b64_tr_b16 v[128:129], v158 offset:13312
	ds_read_b64_tr_b16 v[130:131], v158 offset:13824
	ds_read_b64_tr_b16 v[142:143], v158 offset:17408
	ds_read_b64_tr_b16 v[144:145], v158 offset:17920
	ds_read_b64_tr_b16 v[176:177], v158 offset:14336
	ds_read_b64_tr_b16 v[178:179], v158 offset:14848
	ds_read_b64_tr_b16 v[180:181], v158 offset:18432
	ds_read_b64_tr_b16 v[182:183], v158 offset:18944
	s_waitcnt lgkmcnt(4)
	v_mfma_f32_32x32x16_bf16 v[16:31], v[128:131], v[64:67], v[16:31]
	v_mfma_f32_32x32x16_bf16 v[0:15], v[142:145], v[64:67], v[0:15]
	ds_read_b64_tr_b16 v[128:129], v158 offset:15360
	ds_read_b64_tr_b16 v[130:131], v158 offset:15872
	ds_read_b64_tr_b16 v[142:143], v158 offset:19456
	ds_read_b64_tr_b16 v[144:145], v158 offset:19968
	global_load_dwordx4 v[218:221], v171, s[26:27]
	s_cmp_eq_u64 s[36:37], 0
	s_cbranch_scc1 .Lmla_nok1Ao
	global_load_dwordx4 v[222:225], v184, s[26:27]
.Lmla_nok1Ao:
	global_load_dwordx4 v[226:229], v146, s[100:101]
	s_add_u32 s26, s26, 0x3000
	s_addc_u32 s27, s27, 0
	s_add_u32 s100, s100, 0x2000
	s_addc_u32 s101, s101, 0
	v_max3_f32 v248, v96, v97, v98
	v_max3_f32 v249, v112, v113, v114
	v_max3_f32 v248, v248, v99, v100
	v_max3_f32 v249, v249, v115, v116
	v_max3_f32 v248, v248, v101, v102
	v_max3_f32 v249, v249, v117, v118
	v_max3_f32 v248, v248, v103, v104
	v_max3_f32 v249, v249, v119, v120
	v_max3_f32 v248, v248, v105, v106
	v_max3_f32 v249, v249, v121, v122
	v_max3_f32 v248, v248, v107, v108
	v_max3_f32 v249, v249, v123, v124
	v_max3_f32 v248, v248, v109, v110
	v_max3_f32 v249, v249, v125, v126
	s_waitcnt lgkmcnt(4)
	v_mfma_f32_32x32x16_bf16 v[16:31], v[176:179], v[68:71], v[16:31]
	v_mfma_f32_32x32x16_bf16 v[0:15], v[180:183], v[68:71], v[0:15]
	ds_read_b64_tr_b16 v[176:177], v158 offset:16384
	ds_read_b64_tr_b16 v[178:179], v158 offset:16896
	ds_read_b64_tr_b16 v[180:181], v158 offset:20480
	ds_read_b64_tr_b16 v[182:183], v158 offset:20992
	v_max3_f32 v248, v248, v111, v127
	v_max_f32_e32 v248, v248, v249
	v_mov_b32_e32 v251, v248
	s_nop 1
	v_permlane32_swap_b32_e32 v248, v251
	v_max_f32_e32 v167, v248, v251
	v_cmp_lt_f32_e32 vcc, s72, v167
	s_cbranch_vccnz .Lmla_rescBo

; #define LAS __attribute__((address_space(3)))
; __device__ __forceinline__ void softmax_blk(f32x16& p0, f32x16& p1, f32x16& o0, f32x16& o1, float& mhat, float& lrun, u32x4 (&pf)[4], bool first) {
;     float r0 = max2_(p0[0], p0[1]), r1 = max2_(p1[0], p1[1]);
; #pragma unroll
;     for (int e = 2; e < 16; ++e) { r0 = max2_(r0, p0[e]); r1 = max2_(r1, p1[e]); }
;     const float rm = swap_max(max2_(r0, r1));
;     if (first || __any(rm - mhat > THR)) {
;         const float mn = first ? rm : fmaxf(rm, mhat); const float f = first ? 0.f : __builtin_amdgcn_exp2f(mhat - mn); mhat = mn; lrun *= f;
; #pragma unroll
;         for (int e = 0; e < 16; ++e) { o0[e] *= f; o1[e] *= f; }
;     }
;     float s0 = 0.f, s1 = 0.f;
; #pragma unroll
;     for (int e = 0; e < 16; ++e) { p0[e] = __builtin_amdgcn_exp2f(p0[e] - mhat); p1[e] = __builtin_amdgcn_exp2f(p1[e] - mhat); s0 += p0[e]; s1 += p1[e]; }
;     lrun += s0 + s1;
;     pf[0] = MLA_PACK(p0, 0); pf[1] = MLA_PACK(p0, 8); pf[2] = MLA_PACK(p1, 0); pf[3] = MLA_PACK(p1, 8);
; }
; __device__ __forceinline__ void pv_blk(const u32x4 (&pf)[4], f32x16& o0, f32x16& o1, LAS const unsigned char* vbase) {
; #pragma unroll
;     for (int ks = 0; ks < 4; ++ks) {
;         const bf16x8 p = __builtin_bit_cast(bf16x8, pf[ks]);
;         { const s16x4 lo = vtr(vbase + ks * 1024), hh = vtr(vbase + ks * 1024 + 512); const bf16x8 vf = {lo[0], lo[1], lo[2], lo[3], hh[0], hh[1], hh[2], hh[3]};
;           o0 = __builtin_amdgcn_mfma_f32_32x32x16_bf16(vf, p, o0, 0, 0, 0); }
;         { const s16x4 lo = vtr(vbase + 4096 + ks * 1024), hh = vtr(vbase + 4096 + ks * 1024 + 512); const bf16x8 vf = {lo[0], lo[1], lo[2], lo[3], hh[0], hh[1], hh[2], hh[3]};
;           o1 = __builtin_amdgcn_mfma_f32_32x32x16_bf16(vf, p, o1, 0, 0, 0); }
;     }
; }
; __device__ __forceinline__ void attn_unit(const bf16_t* Qh, const bf16_t* Kh, const bf16_t* Vh, bf16_t* Oh  , int S, int qb, LAS unsigned char* lds, int tid) {
;     ...
;     for (int t = 0; t < NT; ++t) {
;         const unsigned cur = (unsigned)(t & 1) * BUF, nxt = BUF - cur;
;         const int tn = t + 1 < NT ? t + 1 : t;
;         ka = GLD(u32x4, Kg + (size_t)tn * 768 + kc0); kb = GLD(u32x4, Kg + (size_t)tn * 768 + kc1); va = GLD(u32x4, Vg + (size_t)tn * 512 + tid);
;         u32x4 pf[4];
;         {
;             f32x16 p0 = {}, p1 = {};
; #pragma unroll
;             for (int s = 0; s < 6; ++s) {
.Lmla_rescAo_back:
	v_exp_f32_e32 v64, v64
	v_exp_f32_e32 v65, v65
	v_exp_f32_e32 v66, v66
	s_waitcnt lgkmcnt(4)
	v_mfma_f32_32x32x16_bf16 v[48:63], v[128:131], v[104:107], v[48:63]
	v_mfma_f32_32x32x16_bf16 v[32:47], v[142:145], v[104:107], v[32:47]
	ds_read_b128 v[128:131], v155 offset:21504
	ds_read_b128 v[142:145], v155 offset:28160
	ds_read_b128 v[162:165], v135 offset:49152
	v_exp_f32_e32 v67, v67
	v_exp_f32_e32 v68, v68
	v_exp_f32_e32 v69, v69
	v_exp_f32_e32 v70, v70
	v_exp_f32_e32 v71, v71
	v_add_f32_e32 v166, v64, v65
	v_add_f32_e32 v140, v140, v66
	v_add_f32_e32 v166, v166, v67
	s_waitcnt lgkmcnt(3)
	v_mfma_f32_32x32x16_bf16 v[48:63], v[176:179], v[108:111], v[48:63]
	v_mfma_f32_32x32x16_bf16 v[32:47], v[180:183], v[108:111], v[32:47]
	ds_read_b128 v[176:179], v155 offset:21536
	ds_read_b128 v[180:183], v155 offset:28192
	ds_read_b128 v[186:189], v135 offset:50176
	v_cvt_pk_bf16_f32 v64, v64, v65
	v_cvt_pk_bf16_f32 v65, v66, v67
	v_exp_f32_e32 v72, v72
	v_exp_f32_e32 v73, v73
	v_exp_f32_e32 v74, v74
	v_exp_f32_e32 v75, v75
	v_add_f32_e32 v140, v140, v68
	v_add_f32_e32 v166, v166, v69
	v_add_f32_e32 v140, v140, v70
	s_waitcnt lgkmcnt(3)
	v_mfma_f32_32x32x16_bf16 v[96:111], v[128:131], v[162:165], v[190:205]
	v_mfma_f32_32x32x16_bf16 v[112:127], v[142:145], v[162:165], v[190:205]
	ds_read_b128 v[128:131], v155 offset:21568
	ds_read_b128 v[142:145], v155 offset:28224
	ds_read_b128 v[162:165], v135 offset:51200
	v_add_f32_e32 v166, v166, v71
	v_cvt_pk_bf16_f32 v66, v68, v69
	v_cvt_pk_bf16_f32 v67, v70, v71
	v_exp_f32_e32 v76, v76
	v_exp_f32_e32 v77, v77
	v_exp_f32_e32 v78, v78
	v_exp_f32_e32 v79, v79
	v_add_f32_e32 v140, v140, v72
	v_add_f32_e32 v166, v166, v73
	s_waitcnt lgkmcnt(3)
	v_mfma_f32_32x32x16_bf16 v[96:111], v[176:179], v[186:189], v[96:111]
	v_mfma_f32_32x32x16_bf16 v[112:127], v[180:183], v[186:189], v[112:127]
	ds_read_b128 v[176:179], v155 offset:21600
	ds_read_b128 v[180:183], v155 offset:28256
	ds_read_b128 v[186:189], v135 offset:52224
	v_add_f32_e32 v140, v140, v74
	v_add_f32_e32 v166, v166, v75
	v_cvt_pk_bf16_f32 v68, v72, v73
	v_cvt_pk_bf16_f32 v69, v74, v75
	v_exp_f32_e32 v80, v80
	v_exp_f32_e32 v81, v81
	v_exp_f32_e32 v82, v82
	v_exp_f32_e32 v83, v83
	v_add_f32_e32 v140, v140, v76
	v_add_f32_e32 v166, v166, v77
	s_waitcnt lgkmcnt(3)
	v_mfma_f32_32x32x16_bf16 v[96:111], v[128:131], v[162:165], v[96:111]
	v_mfma_f32_32x32x16_bf16 v[112:127], v[142:145], v[162:165], v[112:127]
	ds_read_b128 v[128:131], v155 offset:21632
	ds_read_b128 v[142:145], v155 offset:28288
	ds_read_b128 v[162:165], v135 offset:53248
	v_add_f32_e32 v140, v140, v78
	v_add_f32_e32 v166, v166, v79
	v_cvt_pk_bf16_f32 v70, v76, v77
	v_cvt_pk_bf16_f32 v71, v78, v79
	v_exp_f32_e32 v84, v84
	v_exp_f32_e32 v85, v85
	v_exp_f32_e32 v86, v86
	v_exp_f32_e32 v87, v87
	v_add_f32_e32 v140, v140, v80
	s_waitcnt lgkmcnt(3)
	v_mfma_f32_32x32x16_bf16 v[96:111], v[176:179], v[186:189], v[96:111]
	v_mfma_f32_32x32x16_bf16 v[112:127], v[180:183], v[186:189], v[112:127]
	ds_read_b128 v[176:179], v155 offset:21664
	ds_read_b128 v[180:183], v155 offset:28320
	ds_read_b128 v[186:189], v135 offset:54272
	v_add_f32_e32 v166, v166, v81
	v_add_f32_e32 v140, v140, v82
	v_add_f32_e32 v166, v166, v83
	v_cvt_pk_bf16_f32 v72, v80, v81
	v_cvt_pk_bf16_f32 v73, v82, v83
	v_exp_f32_e32 v88, v88
	v_exp_f32_e32 v89, v89
	v_exp_f32_e32 v90, v90
	v_exp_f32_e32 v91, v91
	v_add_f32_e32 v140, v140, v84
	s_waitcnt vmcnt(0)
	ds_write_b128 v150, v[218:221]
	ds_write_b128 v156, v[222:225]
	ds_write_b128 v157, v[226:229] offset:34816
	s_waitcnt lgkmcnt(6)
	v_mfma_f32_32x32x16_bf16 v[96:111], v[128:131], v[162:165], v[96:111]
	v_mfma_f32_32x32x16_bf16 v[112:127], v[142:145], v[162:165], v[112:127]
	v_add_f32_e32 v166, v166, v85
	v_add_f32_e32 v140, v140, v86
	v_add_f32_e32 v166, v166, v87
	v_cvt_pk_bf16_f32 v74, v84, v85
	v_cvt_pk_bf16_f32 v75, v86, v87
	v_exp_f32_e32 v92, v92
	v_exp_f32_e32 v93, v93
	v_exp_f32_e32 v94, v94
	v_exp_f32_e32 v95, v95
	s_waitcnt lgkmcnt(3)
	v_mfma_f32_32x32x16_bf16 v[96:111], v[176:179], v[186:189], v[96:111]
	v_mfma_f32_32x32x16_bf16 v[112:127], v[180:183], v[186:189], v[112:127]
	v_add_f32_e32 v140, v140, v88
	v_add_f32_e32 v166, v166, v89
	v_add_f32_e32 v140, v140, v90
	v_add_f32_e32 v166, v166, v91
	v_cvt_pk_bf16_f32 v76, v88, v89
	v_cvt_pk_bf16_f32 v77, v90, v91
	v_add_f32_e32 v140, v140, v92
	v_add_f32_e32 v166, v166, v93
	v_add_f32_e32 v140, v140, v94
	v_add_f32_e32 v166, v166, v95
	v_cvt_pk_bf16_f32 v78, v92, v93
	v_cvt_pk_bf16_f32 v79, v94, v95
	v_add_f32_e32 v140, v140, v166
	s_waitcnt lgkmcnt(0)
	s_barrier
	s_add_i32 s1, s1, 1
	s_cmp_lg_u32 s1, s18
	s_cbranch_scc0 .Lmla_epi
	ds_read_b64_tr_b16 v[128:129], v158 offset:34816
	ds_read_b64_tr_b16 v[130:131], v158 offset:35328
	ds_read_b64_tr_b16 v[142:143], v158 offset:38912
	ds_read_b64_tr_b16 v[144:145], v158 offset:39424
	ds_read_b64_tr_b16 v[176:177], v158 offset:35840
	ds_read_b64_tr_b16 v[178:179], v158 offset:36352
	ds_read_b64_tr_b16 v[180:181], v158 offset:39936
	ds_read_b64_tr_b16 v[182:183], v158 offset:40448
	s_waitcnt lgkmcnt(4)
	v_mfma_f32_32x32x16_bf16 v[16:31], v[128:131], v[64:67], v[16:31]
	v_mfma_f32_32x32x16_bf16 v[0:15], v[142:145], v[64:67], v[0:15]
	ds_read_b64_tr_b16 v[128:129], v158 offset:36864
	ds_read_b64_tr_b16 v[130:131], v158 offset:37376
	ds_read_b64_tr_b16 v[142:143], v158 offset:40960
	ds_read_b64_tr_b16 v[144:145], v158 offset:41472
	global_load_dwordx4 v[218:221], v171, s[26:27]
	s_cmp_eq_u64 s[36:37], 0
	s_cbranch_scc1 .Lmla_nok1Ae
	global_load_dwordx4 v[222:225], v184, s[26:27]
.Lmla_nok1Ae:
	global_load_dwordx4 v[226:229], v146, s[100:101]
	s_add_u32 s26, s26, 0x3000
	s_addc_u32 s27, s27, 0
	s_add_u32 s100, s100, 0x2000
	s_addc_u32 s101, s101, 0
	v_max3_f32 v248, v96, v97, v98
	v_max3_f32 v249, v112, v113, v114
	v_max3_f32 v248, v248, v99, v100
	v_max3_f32 v249, v249, v115, v116
	v_max3_f32 v248, v248, v101, v102
	v_max3_f32 v249, v249, v117, v118
	v_max3_f32 v248, v248, v103, v104
	v_max3_f32 v249, v249, v119, v120
	v_max3_f32 v248, v248, v105, v106
	v_max3_f32 v249, v249, v121, v122
	v_max3_f32 v248, v248, v107, v108
	v_max3_f32 v249, v249, v123, v124
	v_max3_f32 v248, v248, v109, v110
	v_max3_f32 v249, v249, v125, v126
	s_waitcnt lgkmcnt(4)
	v_mfma_f32_32x32x16_bf16 v[16:31], v[176:179], v[68:71], v[16:31]
	v_mfma_f32_32x32x16_bf16 v[0:15], v[180:183], v[68:71], v[0:15]
	ds_read_b64_tr_b16 v[176:177], v158 offset:37888
	ds_read_b64_tr_b16 v[178:179], v158 offset:38400
	ds_read_b64_tr_b16 v[180:181], v158 offset:41984
	ds_read_b64_tr_b16 v[182:183], v158 offset:42496
	v_max3_f32 v248, v248, v111, v127
	v_max_f32_e32 v248, v248, v249
	v_mov_b32_e32 v251, v248
	s_nop 1
	v_permlane32_swap_b32_e32 v248, v251
	v_max_f32_e32 v167, v248, v251
	v_cmp_lt_f32_e32 vcc, s72, v167
	s_cbranch_vccnz .Lmla_rescBv
